# G3/G5 loops: next slice's A fragments read in the first half-step (three or four of the six prefetch reads moved half a slice earlier)
# baseline (speedup 1.0000x reference)
.Lgf_G5x_top:
	s_waitcnt vmcnt(3)
	s_waitcnt lgkmcnt(0)
	s_barrier
	v_mfma_f32_16x16x32_bf16 v[102:105], v[2:5], v[26:29], v[102:105]
	v_mfma_f32_16x16x32_bf16 v[98:101], v[6:9], v[26:29], v[98:101]
	s_add_i32 s17, s8, -3
	s_and_b32 s19, s17, 2
	s_mulk_i32 s19, 0x6000
	v_add_u32_e32 v110, s19, v142
	ds_read_b128 v[106:109], v110
	v_mfma_f32_16x16x32_bf16 v[86:89], v[10:13], v[26:29], v[86:89]
	ds_read_b128 v[144:147], v110 offset:1024
	s_and_b32 s89, s8, 3
	s_mulk_i32 s89, 0x6000
	s_add_i32 s89, s89, s88
	s_mov_b32 m0, s89
	s_add_i32 s26, s8, -2
	s_and_b32 s28, s26, 3
	s_mulk_i32 s28, 0x6000
	v_add_u32_e32 v127, s28, v140
	v_add_u32_e32 v143, s28, v141
	v_mfma_f32_16x16x32_bf16 v[70:73], v[14:17], v[26:29], v[70:73]
	ds_read_b128 v[118:121], v127
	v_mfma_f32_16x16x32_bf16 v[90:93], v[2:5], v[22:25], v[90:93]
	ds_read_b128 v[114:117], v127 offset:1024
	global_load_lds_dwordx4 v126, s[90:91]
	s_add_i32 m0, s89, 0x2000
	v_mfma_f32_16x16x32_bf16 v[78:81], v[6:9], v[22:25], v[78:81]
	ds_read_b128 v[110:113], v127 offset:2048
	global_load_lds_dwordx4 v128, s[90:91]
	s_add_i32 m0, s89, 0x4000
	v_mfma_f32_16x16x32_bf16 v[62:65], v[10:13], v[22:25], v[62:65]
	global_load_lds_dwordx4 v130, s[92:93]
	s_add_u32 s90, s90, 64
	s_addc_u32 s91, s91, 0
	s_add_u32 s92, s92, 64
	s_addc_u32 s93, s93, 0
	v_mfma_f32_16x16x32_bf16 v[50:53], v[14:17], v[22:25], v[50:53]
	s_waitcnt lgkmcnt(0)
	v_mfma_f32_16x16x32_bf16 v[74:77], v[2:5], v[106:109], v[74:77]
	ds_read_b128 v[26:29], v143
	v_mfma_f32_16x16x32_bf16 v[58:61], v[6:9], v[106:109], v[58:61]
	ds_read_b128 v[22:25], v143 offset:1024
	v_mfma_f32_16x16x32_bf16 v[38:41], v[10:13], v[106:109], v[38:41]
	v_mfma_f32_16x16x32_bf16 v[30:33], v[14:17], v[106:109], v[30:33]
	ds_read_b128 v[106:109], v127 offset:3072
	v_mfma_f32_16x16x32_bf16 v[94:97], v[2:5], v[144:147], v[94:97]
	v_mfma_f32_16x16x32_bf16 v[82:85], v[6:9], v[144:147], v[82:85]
	v_mfma_f32_16x16x32_bf16 v[66:69], v[10:13], v[144:147], v[66:69]
	v_mfma_f32_16x16x32_bf16 v[34:37], v[14:17], v[144:147], v[34:37]
	s_waitcnt vmcnt(3)
	s_waitcnt lgkmcnt(0)
	s_barrier
	v_mfma_f32_16x16x32_bf16 v[102:105], v[118:121], v[26:29], v[102:105]
	v_mfma_f32_16x16x32_bf16 v[98:101], v[114:117], v[26:29], v[98:101]
	v_add_u32_e32 v132, s28, v142
	ds_read_b128 v[144:147], v132
	v_mfma_f32_16x16x32_bf16 v[86:89], v[110:113], v[26:29], v[86:89]
	ds_read_b128 v[122:125], v132 offset:1024
	s_add_i32 s89, s19, s88
	s_mov_b32 m0, s89
	s_add_i32 s19, s8, -1
	s_and_b32 s19, s19, 2
	s_mulk_i32 s19, 0x6000
	v_add_u32_e32 v127, s19, v140
	v_add_u32_e32 v132, s19, v141
	v_mfma_f32_16x16x32_bf16 v[70:73], v[106:109], v[26:29], v[70:73]
	ds_read_b128 v[2:5], v127
	v_mfma_f32_16x16x32_bf16 v[90:93], v[118:121], v[22:25], v[90:93]
	ds_read_b128 v[6:9], v127 offset:1024
	global_load_lds_dwordx4 v126, s[90:91]
	s_add_i32 m0, s89, 0x2000
	v_mfma_f32_16x16x32_bf16 v[78:81], v[114:117], v[22:25], v[78:81]
	ds_read_b128 v[10:13], v127 offset:2048
	global_load_lds_dwordx4 v128, s[90:91]
	s_add_i32 m0, s89, 0x4000
	v_mfma_f32_16x16x32_bf16 v[62:65], v[110:113], v[22:25], v[62:65]
	ds_read_b128 v[14:17], v127 offset:3072
	global_load_lds_dwordx4 v130, s[92:93]
	s_add_u32 s90, s90, 64
	s_addc_u32 s91, s91, 0
	s_add_u32 s92, s92, 64
	s_addc_u32 s93, s93, 0
	v_mfma_f32_16x16x32_bf16 v[50:53], v[106:109], v[22:25], v[50:53]
	s_waitcnt lgkmcnt(0)
	v_mfma_f32_16x16x32_bf16 v[74:77], v[118:121], v[144:147], v[74:77]
	ds_read_b128 v[26:29], v132
	v_mfma_f32_16x16x32_bf16 v[58:61], v[114:117], v[144:147], v[58:61]
	ds_read_b128 v[22:25], v132 offset:1024
	v_mfma_f32_16x16x32_bf16 v[38:41], v[110:113], v[144:147], v[38:41]
	v_mfma_f32_16x16x32_bf16 v[30:33], v[106:109], v[144:147], v[30:33]
	s_add_u32 s20, s20, 0x80
	s_addc_u32 s21, s21, 0
	s_add_i32 s8, s8, 2
	s_cmpk_gt_u32 s17, 0x55
	v_mfma_f32_16x16x32_bf16 v[94:97], v[118:121], v[122:125], v[94:97]
	v_mfma_f32_16x16x32_bf16 v[82:85], v[114:117], v[122:125], v[82:85]
	v_mfma_f32_16x16x32_bf16 v[66:69], v[110:113], v[122:125], v[66:69]
	v_mfma_f32_16x16x32_bf16 v[34:37], v[106:109], v[122:125], v[34:37]
	s_cmp_lt_u32 s8, 86
	s_cbranch_scc1 .Lgf_G5x_top
	s_waitcnt vmcnt(3)
	s_waitcnt lgkmcnt(0)
	s_barrier
	v_mfma_f32_16x16x32_bf16 v[102:105], v[2:5], v[26:29], v[102:105]
	v_mfma_f32_16x16x32_bf16 v[98:101], v[6:9], v[26:29], v[98:101]
	s_add_i32 s17, s8, -3
	s_and_b32 s19, s17, 2
	s_mulk_i32 s19, 0x6000
	v_add_u32_e32 v110, s19, v142
	ds_read_b128 v[106:109], v110
	v_mfma_f32_16x16x32_bf16 v[86:89], v[10:13], v[26:29], v[86:89]
	ds_read_b128 v[144:147], v110 offset:1024
	s_and_b32 s89, s8, 3
	s_mulk_i32 s89, 0x6000
	s_add_i32 s89, s89, s88
	s_mov_b32 m0, s89
	s_add_i32 s26, s8, -2
	s_and_b32 s28, s26, 3
	s_mulk_i32 s28, 0x6000
	v_add_u32_e32 v127, s28, v140
	v_add_u32_e32 v143, s28, v141
	v_mfma_f32_16x16x32_bf16 v[70:73], v[14:17], v[26:29], v[70:73]
	ds_read_b128 v[118:121], v127
	v_mfma_f32_16x16x32_bf16 v[90:93], v[2:5], v[22:25], v[90:93]
	ds_read_b128 v[114:117], v127 offset:1024
	global_load_lds_dwordx4 v126, s[90:91]
	s_add_i32 m0, s89, 0x2000
	v_mfma_f32_16x16x32_bf16 v[78:81], v[6:9], v[22:25], v[78:81]
	ds_read_b128 v[110:113], v127 offset:2048
	global_load_lds_dwordx4 v128, s[90:91]
	s_add_i32 m0, s89, 0x4000
	v_mfma_f32_16x16x32_bf16 v[62:65], v[10:13], v[22:25], v[62:65]
	global_load_lds_dwordx4 v130, s[92:93]
	s_add_u32 s90, s90, 64
	s_addc_u32 s91, s91, 0
	s_add_u32 s92, s92, 64
	s_addc_u32 s93, s93, 0
	v_mfma_f32_16x16x32_bf16 v[50:53], v[14:17], v[22:25], v[50:53]
	s_waitcnt lgkmcnt(0)
	v_mfma_f32_16x16x32_bf16 v[74:77], v[2:5], v[106:109], v[74:77]
	ds_read_b128 v[26:29], v143
	v_mfma_f32_16x16x32_bf16 v[58:61], v[6:9], v[106:109], v[58:61]
	ds_read_b128 v[22:25], v143 offset:1024
	v_mfma_f32_16x16x32_bf16 v[38:41], v[10:13], v[106:109], v[38:41]
	v_mfma_f32_16x16x32_bf16 v[30:33], v[14:17], v[106:109], v[30:33]
	ds_read_b128 v[106:109], v127 offset:3072
	v_mfma_f32_16x16x32_bf16 v[94:97], v[2:5], v[144:147], v[94:97]
	v_mfma_f32_16x16x32_bf16 v[82:85], v[6:9], v[144:147], v[82:85]
	v_mfma_f32_16x16x32_bf16 v[66:69], v[10:13], v[144:147], v[66:69]
	v_mfma_f32_16x16x32_bf16 v[34:37], v[14:17], v[144:147], v[34:37]
	s_waitcnt vmcnt(3)
	s_waitcnt lgkmcnt(0)
	s_barrier
	v_mfma_f32_16x16x32_bf16 v[102:105], v[118:121], v[26:29], v[102:105]
	v_mfma_f32_16x16x32_bf16 v[98:101], v[114:117], v[26:29], v[98:101]
	v_add_u32_e32 v132, s28, v142
	ds_read_b128 v[144:147], v132
	v_mfma_f32_16x16x32_bf16 v[86:89], v[110:113], v[26:29], v[86:89]
	ds_read_b128 v[122:125], v132 offset:1024
	s_add_i32 s19, s8, -1
	s_and_b32 s19, s19, 2
	s_mulk_i32 s19, 0x6000
	v_add_u32_e32 v127, s19, v140
	v_add_u32_e32 v132, s19, v141
	v_mfma_f32_16x16x32_bf16 v[70:73], v[106:109], v[26:29], v[70:73]
	ds_read_b128 v[2:5], v127
	v_mfma_f32_16x16x32_bf16 v[90:93], v[118:121], v[22:25], v[90:93]
	ds_read_b128 v[6:9], v127 offset:1024
	v_mfma_f32_16x16x32_bf16 v[78:81], v[114:117], v[22:25], v[78:81]
	ds_read_b128 v[10:13], v127 offset:2048
	v_mfma_f32_16x16x32_bf16 v[62:65], v[110:113], v[22:25], v[62:65]
	ds_read_b128 v[14:17], v127 offset:3072
	v_mfma_f32_16x16x32_bf16 v[50:53], v[106:109], v[22:25], v[50:53]
	s_waitcnt lgkmcnt(0)
	v_mfma_f32_16x16x32_bf16 v[74:77], v[118:121], v[144:147], v[74:77]
	ds_read_b128 v[26:29], v132
	v_mfma_f32_16x16x32_bf16 v[58:61], v[114:117], v[144:147], v[58:61]
	ds_read_b128 v[22:25], v132 offset:1024
	v_mfma_f32_16x16x32_bf16 v[38:41], v[110:113], v[144:147], v[38:41]
	v_mfma_f32_16x16x32_bf16 v[30:33], v[106:109], v[144:147], v[30:33]
	s_add_u32 s20, s20, 0x80
	s_addc_u32 s21, s21, 0
	s_add_i32 s8, s8, 2
	s_cmpk_gt_u32 s17, 0x55
	v_mfma_f32_16x16x32_bf16 v[94:97], v[118:121], v[122:125], v[94:97]
	v_mfma_f32_16x16x32_bf16 v[82:85], v[114:117], v[122:125], v[82:85]
	v_mfma_f32_16x16x32_bf16 v[66:69], v[110:113], v[122:125], v[66:69]
	v_mfma_f32_16x16x32_bf16 v[34:37], v[106:109], v[122:125], v[34:37]
	s_waitcnt vmcnt(0)
	s_waitcnt lgkmcnt(0)
	s_barrier
	v_mfma_f32_16x16x32_bf16 v[102:105], v[2:5], v[26:29], v[102:105]
	v_mfma_f32_16x16x32_bf16 v[98:101], v[6:9], v[26:29], v[98:101]
	s_add_i32 s17, s8, -3
	s_and_b32 s19, s17, 2
	s_mulk_i32 s19, 0x6000
	v_add_u32_e32 v110, s19, v142
	ds_read_b128 v[106:109], v110
	v_mfma_f32_16x16x32_bf16 v[86:89], v[10:13], v[26:29], v[86:89]
	ds_read_b128 v[144:147], v110 offset:1024
	s_add_i32 s26, s8, -2
	s_and_b32 s28, s26, 3
	s_mulk_i32 s28, 0x6000
	v_add_u32_e32 v127, s28, v140
	v_add_u32_e32 v143, s28, v141
	v_mfma_f32_16x16x32_bf16 v[70:73], v[14:17], v[26:29], v[70:73]
	ds_read_b128 v[118:121], v127
	v_mfma_f32_16x16x32_bf16 v[90:93], v[2:5], v[22:25], v[90:93]
	ds_read_b128 v[114:117], v127 offset:1024
	v_mfma_f32_16x16x32_bf16 v[78:81], v[6:9], v[22:25], v[78:81]
	ds_read_b128 v[110:113], v127 offset:2048
	v_mfma_f32_16x16x32_bf16 v[62:65], v[10:13], v[22:25], v[62:65]
	v_mfma_f32_16x16x32_bf16 v[50:53], v[14:17], v[22:25], v[50:53]
	s_waitcnt lgkmcnt(0)
	v_mfma_f32_16x16x32_bf16 v[74:77], v[2:5], v[106:109], v[74:77]
	ds_read_b128 v[26:29], v143
	v_mfma_f32_16x16x32_bf16 v[58:61], v[6:9], v[106:109], v[58:61]
	ds_read_b128 v[22:25], v143 offset:1024
	v_mfma_f32_16x16x32_bf16 v[38:41], v[10:13], v[106:109], v[38:41]
	v_mfma_f32_16x16x32_bf16 v[30:33], v[14:17], v[106:109], v[30:33]
	ds_read_b128 v[106:109], v127 offset:3072
	v_mfma_f32_16x16x32_bf16 v[94:97], v[2:5], v[144:147], v[94:97]
	v_mfma_f32_16x16x32_bf16 v[82:85], v[6:9], v[144:147], v[82:85]
	v_mfma_f32_16x16x32_bf16 v[66:69], v[10:13], v[144:147], v[66:69]
	v_mfma_f32_16x16x32_bf16 v[34:37], v[14:17], v[144:147], v[34:37]
	s_waitcnt vmcnt(0)
	s_waitcnt lgkmcnt(0)
	s_barrier
	v_mfma_f32_16x16x32_bf16 v[102:105], v[118:121], v[26:29], v[102:105]
	v_mfma_f32_16x16x32_bf16 v[98:101], v[114:117], v[26:29], v[98:101]
	v_add_u32_e32 v132, s28, v142
	ds_read_b128 v[144:147], v132
	v_mfma_f32_16x16x32_bf16 v[86:89], v[110:113], v[26:29], v[86:89]
	ds_read_b128 v[122:125], v132 offset:1024
	v_mfma_f32_16x16x32_bf16 v[70:73], v[106:109], v[26:29], v[70:73]
	v_mfma_f32_16x16x32_bf16 v[90:93], v[118:121], v[22:25], v[90:93]
	v_mfma_f32_16x16x32_bf16 v[78:81], v[114:117], v[22:25], v[78:81]
	v_mfma_f32_16x16x32_bf16 v[62:65], v[110:113], v[22:25], v[62:65]
	v_mfma_f32_16x16x32_bf16 v[50:53], v[106:109], v[22:25], v[50:53]
	s_waitcnt lgkmcnt(0)
	v_mfma_f32_16x16x32_bf16 v[74:77], v[118:121], v[144:147], v[74:77]
	v_mfma_f32_16x16x32_bf16 v[58:61], v[114:117], v[144:147], v[58:61]
	v_mfma_f32_16x16x32_bf16 v[38:41], v[110:113], v[144:147], v[38:41]
	v_mfma_f32_16x16x32_bf16 v[30:33], v[106:109], v[144:147], v[30:33]
	s_add_u32 s20, s20, 0x80
	s_addc_u32 s21, s21, 0
	s_add_i32 s8, s8, 2
	s_cmpk_gt_u32 s17, 0x55
	v_mfma_f32_16x16x32_bf16 v[94:97], v[118:121], v[122:125], v[94:97]
	v_mfma_f32_16x16x32_bf16 v[82:85], v[114:117], v[122:125], v[82:85]
	v_mfma_f32_16x16x32_bf16 v[66:69], v[110:113], v[122:125], v[66:69]
	v_mfma_f32_16x16x32_bf16 v[34:37], v[106:109], v[122:125], v[34:37]
	s_branch .LBB0_135
.Lgr_G5x_entry:
	s_waitcnt vmcnt(3)
	s_waitcnt lgkmcnt(0)
	s_barrier
	v_mfma_f32_16x16x32_bf16 v[102:105], v[2:5], v[26:29], v[102:105]
	v_mfma_f32_16x16x32_bf16 v[98:101], v[6:9], v[26:29], v[98:101]
	s_add_i32 s17, s8, -3
	s_and_b32 s19, s17, 2
	s_mulk_i32 s19, 0x6000
	v_add_u32_e32 v110, s19, v142
	ds_read_b128 v[106:109], v110
	v_mfma_f32_16x16x32_bf16 v[86:89], v[10:13], v[26:29], v[86:89]
	ds_read_b128 v[144:147], v110 offset:1024
	s_and_b32 s89, s8, 3
	s_mulk_i32 s89, 0x6000
	s_add_i32 s89, s89, s88
	s_mov_b32 m0, s89
	s_add_i32 s26, s8, -2
	s_and_b32 s28, s26, 3
	s_mulk_i32 s28, 0x6000
	v_add_u32_e32 v127, s28, v140
	v_add_u32_e32 v143, s28, v141
	v_mfma_f32_16x16x32_bf16 v[70:73], v[14:17], v[26:29], v[70:73]
	ds_read_b128 v[118:121], v127
	v_mfma_f32_16x16x32_bf16 v[90:93], v[2:5], v[22:25], v[90:93]
	ds_read_b128 v[114:117], v127 offset:1024
	global_load_lds_dwordx4 v126, s[90:91]
	s_add_i32 m0, s89, 0x2000
	v_mfma_f32_16x16x32_bf16 v[78:81], v[6:9], v[22:25], v[78:81]
	ds_read_b128 v[110:113], v127 offset:2048
	global_load_lds_dwordx4 v128, s[90:91]
	s_add_i32 m0, s89, 0x4000
	v_mfma_f32_16x16x32_bf16 v[62:65], v[10:13], v[22:25], v[62:65]
	global_load_lds_dwordx4 v130, s[92:93]
	s_add_u32 s90, s90, 64
	s_addc_u32 s91, s91, 0
	s_add_u32 s92, s92, 64
	s_addc_u32 s93, s93, 0
	v_mfma_f32_16x16x32_bf16 v[50:53], v[14:17], v[22:25], v[50:53]
	s_waitcnt vmcnt(3)
	s_waitcnt lgkmcnt(0)
	s_barrier
	v_mfma_f32_16x16x32_bf16 v[74:77], v[2:5], v[106:109], v[74:77]
	ds_read_b128 v[26:29], v143
	v_mfma_f32_16x16x32_bf16 v[58:61], v[6:9], v[106:109], v[58:61]
	ds_read_b128 v[22:25], v143 offset:1024
	v_mfma_f32_16x16x32_bf16 v[38:41], v[10:13], v[106:109], v[38:41]
	v_mfma_f32_16x16x32_bf16 v[30:33], v[14:17], v[106:109], v[30:33]
	ds_read_b128 v[106:109], v127 offset:3072
	v_mfma_f32_16x16x32_bf16 v[94:97], v[2:5], v[144:147], v[94:97]
	v_mfma_f32_16x16x32_bf16 v[82:85], v[6:9], v[144:147], v[82:85]
	v_mfma_f32_16x16x32_bf16 v[66:69], v[10:13], v[144:147], v[66:69]
	v_mfma_f32_16x16x32_bf16 v[34:37], v[14:17], v[144:147], v[34:37]
	s_waitcnt lgkmcnt(0)
	v_mfma_f32_16x16x32_bf16 v[102:105], v[118:121], v[26:29], v[102:105]
	v_mfma_f32_16x16x32_bf16 v[98:101], v[114:117], v[26:29], v[98:101]
	v_add_u32_e32 v132, s28, v142
	ds_read_b128 v[144:147], v132
	v_mfma_f32_16x16x32_bf16 v[86:89], v[110:113], v[26:29], v[86:89]
	ds_read_b128 v[122:125], v132 offset:1024
	s_add_i32 s89, s19, s88
	s_mov_b32 m0, s89
	s_add_i32 s19, s8, -1
	s_and_b32 s19, s19, 2
	s_mulk_i32 s19, 0x6000
	v_add_u32_e32 v127, s19, v140
	v_add_u32_e32 v132, s19, v141
	v_mfma_f32_16x16x32_bf16 v[70:73], v[106:109], v[26:29], v[70:73]
	ds_read_b128 v[2:5], v127
	v_mfma_f32_16x16x32_bf16 v[90:93], v[118:121], v[22:25], v[90:93]
	ds_read_b128 v[6:9], v127 offset:1024
	global_load_lds_dwordx4 v126, s[90:91]
	s_add_i32 m0, s89, 0x2000
	v_mfma_f32_16x16x32_bf16 v[78:81], v[114:117], v[22:25], v[78:81]
	ds_read_b128 v[10:13], v127 offset:2048
	global_load_lds_dwordx4 v128, s[90:91]
	s_add_i32 m0, s89, 0x4000
	v_mfma_f32_16x16x32_bf16 v[62:65], v[110:113], v[22:25], v[62:65]
	ds_read_b128 v[14:17], v127 offset:3072
	global_load_lds_dwordx4 v130, s[92:93]
	s_add_u32 s90, s90, 64
	s_addc_u32 s91, s91, 0
	s_add_u32 s92, s92, 64
	s_addc_u32 s93, s93, 0
	v_mfma_f32_16x16x32_bf16 v[50:53], v[106:109], v[22:25], v[50:53]
.Lgr_G5x_top:
	s_waitcnt vmcnt(3)
	s_waitcnt lgkmcnt(0)
	s_barrier
	v_mfma_f32_16x16x32_bf16 v[74:77], v[118:121], v[144:147], v[74:77]
	ds_read_b128 v[26:29], v132
	v_mfma_f32_16x16x32_bf16 v[58:61], v[114:117], v[144:147], v[58:61]
	ds_read_b128 v[22:25], v132 offset:1024
	v_mfma_f32_16x16x32_bf16 v[38:41], v[110:113], v[144:147], v[38:41]
	v_mfma_f32_16x16x32_bf16 v[30:33], v[106:109], v[144:147], v[30:33]
	s_add_u32 s20, s20, 0x80
	s_addc_u32 s21, s21, 0
	s_add_i32 s8, s8, 2
	s_cmpk_gt_u32 s17, 0x55
	v_mfma_f32_16x16x32_bf16 v[94:97], v[118:121], v[122:125], v[94:97]
	v_mfma_f32_16x16x32_bf16 v[82:85], v[114:117], v[122:125], v[82:85]
	v_mfma_f32_16x16x32_bf16 v[66:69], v[110:113], v[122:125], v[66:69]
	v_mfma_f32_16x16x32_bf16 v[34:37], v[106:109], v[122:125], v[34:37]
	s_cmp_lt_u32 s8, 86
	s_cbranch_scc0 .Lgr_G5x_tail
	s_waitcnt lgkmcnt(0)
	v_mfma_f32_16x16x32_bf16 v[102:105], v[2:5], v[26:29], v[102:105]
	v_mfma_f32_16x16x32_bf16 v[98:101], v[6:9], v[26:29], v[98:101]
	s_add_i32 s17, s8, -3
	s_and_b32 s19, s17, 2
	s_mulk_i32 s19, 0x6000
	v_add_u32_e32 v110, s19, v142
	ds_read_b128 v[106:109], v110
	v_mfma_f32_16x16x32_bf16 v[86:89], v[10:13], v[26:29], v[86:89]
	ds_read_b128 v[144:147], v110 offset:1024
	s_and_b32 s89, s8, 3
	s_mulk_i32 s89, 0x6000
	s_add_i32 s89, s89, s88
	s_mov_b32 m0, s89
	s_add_i32 s26, s8, -2
	s_and_b32 s28, s26, 3
	s_mulk_i32 s28, 0x6000
	v_add_u32_e32 v127, s28, v140
	v_add_u32_e32 v143, s28, v141
	v_mfma_f32_16x16x32_bf16 v[70:73], v[14:17], v[26:29], v[70:73]
	ds_read_b128 v[118:121], v127
	v_mfma_f32_16x16x32_bf16 v[90:93], v[2:5], v[22:25], v[90:93]
	ds_read_b128 v[114:117], v127 offset:1024
	global_load_lds_dwordx4 v126, s[90:91]
	s_add_i32 m0, s89, 0x2000
	v_mfma_f32_16x16x32_bf16 v[78:81], v[6:9], v[22:25], v[78:81]
	ds_read_b128 v[110:113], v127 offset:2048
	global_load_lds_dwordx4 v128, s[90:91]
	s_add_i32 m0, s89, 0x4000
	v_mfma_f32_16x16x32_bf16 v[62:65], v[10:13], v[22:25], v[62:65]
	global_load_lds_dwordx4 v130, s[92:93]
	s_add_u32 s90, s90, 64
	s_addc_u32 s91, s91, 0
	s_add_u32 s92, s92, 64
	s_addc_u32 s93, s93, 0
	v_mfma_f32_16x16x32_bf16 v[50:53], v[14:17], v[22:25], v[50:53]
	s_waitcnt vmcnt(3)
	s_waitcnt lgkmcnt(0)
	s_barrier
	v_mfma_f32_16x16x32_bf16 v[74:77], v[2:5], v[106:109], v[74:77]
	ds_read_b128 v[26:29], v143
	v_mfma_f32_16x16x32_bf16 v[58:61], v[6:9], v[106:109], v[58:61]
	ds_read_b128 v[22:25], v143 offset:1024
	v_mfma_f32_16x16x32_bf16 v[38:41], v[10:13], v[106:109], v[38:41]
	v_mfma_f32_16x16x32_bf16 v[30:33], v[14:17], v[106:109], v[30:33]
	ds_read_b128 v[106:109], v127 offset:3072
	v_mfma_f32_16x16x32_bf16 v[94:97], v[2:5], v[144:147], v[94:97]
	v_mfma_f32_16x16x32_bf16 v[82:85], v[6:9], v[144:147], v[82:85]
	v_mfma_f32_16x16x32_bf16 v[66:69], v[10:13], v[144:147], v[66:69]
	v_mfma_f32_16x16x32_bf16 v[34:37], v[14:17], v[144:147], v[34:37]
	s_waitcnt lgkmcnt(0)
	v_mfma_f32_16x16x32_bf16 v[102:105], v[118:121], v[26:29], v[102:105]
	v_mfma_f32_16x16x32_bf16 v[98:101], v[114:117], v[26:29], v[98:101]
	v_add_u32_e32 v132, s28, v142
	ds_read_b128 v[144:147], v132
	v_mfma_f32_16x16x32_bf16 v[86:89], v[110:113], v[26:29], v[86:89]
	ds_read_b128 v[122:125], v132 offset:1024
	s_add_i32 s89, s19, s88
	s_mov_b32 m0, s89
	s_add_i32 s19, s8, -1
	s_and_b32 s19, s19, 2
	s_mulk_i32 s19, 0x6000
	v_add_u32_e32 v127, s19, v140
	v_add_u32_e32 v132, s19, v141
	v_mfma_f32_16x16x32_bf16 v[70:73], v[106:109], v[26:29], v[70:73]
	ds_read_b128 v[2:5], v127
	v_mfma_f32_16x16x32_bf16 v[90:93], v[118:121], v[22:25], v[90:93]
	ds_read_b128 v[6:9], v127 offset:1024
	global_load_lds_dwordx4 v126, s[90:91]
	s_add_i32 m0, s89, 0x2000
	v_mfma_f32_16x16x32_bf16 v[78:81], v[114:117], v[22:25], v[78:81]
	ds_read_b128 v[10:13], v127 offset:2048
	global_load_lds_dwordx4 v128, s[90:91]
	s_add_i32 m0, s89, 0x4000
	v_mfma_f32_16x16x32_bf16 v[62:65], v[110:113], v[22:25], v[62:65]
	ds_read_b128 v[14:17], v127 offset:3072
	global_load_lds_dwordx4 v130, s[92:93]
	s_add_u32 s90, s90, 64
	s_addc_u32 s91, s91, 0
	s_add_u32 s92, s92, 64
	s_addc_u32 s93, s93, 0
	v_mfma_f32_16x16x32_bf16 v[50:53], v[106:109], v[22:25], v[50:53]
	s_branch .Lgr_G5x_top
.Lgr_G5x_tail:
	s_waitcnt lgkmcnt(0)
	v_mfma_f32_16x16x32_bf16 v[102:105], v[2:5], v[26:29], v[102:105]
	v_mfma_f32_16x16x32_bf16 v[98:101], v[6:9], v[26:29], v[98:101]
	s_add_i32 s17, s8, -3
	s_and_b32 s19, s17, 2
	s_mulk_i32 s19, 0x6000
	v_add_u32_e32 v110, s19, v142
	ds_read_b128 v[106:109], v110
	v_mfma_f32_16x16x32_bf16 v[86:89], v[10:13], v[26:29], v[86:89]
	ds_read_b128 v[144:147], v110 offset:1024
	s_and_b32 s89, s8, 3
	s_mulk_i32 s89, 0x6000
	s_add_i32 s89, s89, s88
	s_mov_b32 m0, s89
	s_add_i32 s26, s8, -2
	s_and_b32 s28, s26, 3
	s_mulk_i32 s28, 0x6000
	v_add_u32_e32 v127, s28, v140
	v_add_u32_e32 v143, s28, v141
	v_mfma_f32_16x16x32_bf16 v[70:73], v[14:17], v[26:29], v[70:73]
	ds_read_b128 v[118:121], v127
	v_mfma_f32_16x16x32_bf16 v[90:93], v[2:5], v[22:25], v[90:93]
	ds_read_b128 v[114:117], v127 offset:1024
	global_load_lds_dwordx4 v126, s[90:91]
	s_add_i32 m0, s89, 0x2000
	v_mfma_f32_16x16x32_bf16 v[78:81], v[6:9], v[22:25], v[78:81]
	ds_read_b128 v[110:113], v127 offset:2048
	global_load_lds_dwordx4 v128, s[90:91]
	s_add_i32 m0, s89, 0x4000
	v_mfma_f32_16x16x32_bf16 v[62:65], v[10:13], v[22:25], v[62:65]
	global_load_lds_dwordx4 v130, s[92:93]
	s_add_u32 s90, s90, 64
	s_addc_u32 s91, s91, 0
	s_add_u32 s92, s92, 64
	s_addc_u32 s93, s93, 0
	v_mfma_f32_16x16x32_bf16 v[50:53], v[14:17], v[22:25], v[50:53]
	s_waitcnt vmcnt(3)
	s_waitcnt lgkmcnt(0)
	s_barrier
	v_mfma_f32_16x16x32_bf16 v[74:77], v[2:5], v[106:109], v[74:77]
	ds_read_b128 v[26:29], v143
	v_mfma_f32_16x16x32_bf16 v[58:61], v[6:9], v[106:109], v[58:61]
	ds_read_b128 v[22:25], v143 offset:1024
	v_mfma_f32_16x16x32_bf16 v[38:41], v[10:13], v[106:109], v[38:41]
	v_mfma_f32_16x16x32_bf16 v[30:33], v[14:17], v[106:109], v[30:33]
	ds_read_b128 v[106:109], v127 offset:3072
	v_mfma_f32_16x16x32_bf16 v[94:97], v[2:5], v[144:147], v[94:97]
	v_mfma_f32_16x16x32_bf16 v[82:85], v[6:9], v[144:147], v[82:85]
	v_mfma_f32_16x16x32_bf16 v[66:69], v[10:13], v[144:147], v[66:69]
	v_mfma_f32_16x16x32_bf16 v[34:37], v[14:17], v[144:147], v[34:37]
	s_waitcnt lgkmcnt(0)
	v_mfma_f32_16x16x32_bf16 v[102:105], v[118:121], v[26:29], v[102:105]
	v_mfma_f32_16x16x32_bf16 v[98:101], v[114:117], v[26:29], v[98:101]
	v_add_u32_e32 v132, s28, v142
	ds_read_b128 v[144:147], v132
	v_mfma_f32_16x16x32_bf16 v[86:89], v[110:113], v[26:29], v[86:89]
	ds_read_b128 v[122:125], v132 offset:1024
	s_add_i32 s19, s8, -1
	s_and_b32 s19, s19, 2
	s_mulk_i32 s19, 0x6000
	v_add_u32_e32 v127, s19, v140
	v_add_u32_e32 v132, s19, v141
	v_mfma_f32_16x16x32_bf16 v[70:73], v[106:109], v[26:29], v[70:73]
	ds_read_b128 v[2:5], v127
	v_mfma_f32_16x16x32_bf16 v[90:93], v[118:121], v[22:25], v[90:93]
	ds_read_b128 v[6:9], v127 offset:1024
	v_mfma_f32_16x16x32_bf16 v[78:81], v[114:117], v[22:25], v[78:81]
	ds_read_b128 v[10:13], v127 offset:2048
	v_mfma_f32_16x16x32_bf16 v[62:65], v[110:113], v[22:25], v[62:65]
	ds_read_b128 v[14:17], v127 offset:3072
	v_mfma_f32_16x16x32_bf16 v[50:53], v[106:109], v[22:25], v[50:53]
	s_waitcnt vmcnt(0)
	s_waitcnt lgkmcnt(0)
	s_barrier
	v_mfma_f32_16x16x32_bf16 v[74:77], v[118:121], v[144:147], v[74:77]
	ds_read_b128 v[26:29], v132
	v_mfma_f32_16x16x32_bf16 v[58:61], v[114:117], v[144:147], v[58:61]
	ds_read_b128 v[22:25], v132 offset:1024
	v_mfma_f32_16x16x32_bf16 v[38:41], v[110:113], v[144:147], v[38:41]
	v_mfma_f32_16x16x32_bf16 v[30:33], v[106:109], v[144:147], v[30:33]
	s_add_u32 s20, s20, 0x80
	s_addc_u32 s21, s21, 0
	s_add_i32 s8, s8, 2
	s_cmpk_gt_u32 s17, 0x55
	v_mfma_f32_16x16x32_bf16 v[94:97], v[118:121], v[122:125], v[94:97]
	v_mfma_f32_16x16x32_bf16 v[82:85], v[114:117], v[122:125], v[82:85]
	v_mfma_f32_16x16x32_bf16 v[66:69], v[110:113], v[122:125], v[66:69]
	v_mfma_f32_16x16x32_bf16 v[34:37], v[106:109], v[122:125], v[34:37]
	s_waitcnt lgkmcnt(0)
	v_mfma_f32_16x16x32_bf16 v[102:105], v[2:5], v[26:29], v[102:105]
	v_mfma_f32_16x16x32_bf16 v[98:101], v[6:9], v[26:29], v[98:101]
	s_add_i32 s17, s8, -3
	s_and_b32 s19, s17, 2
	s_mulk_i32 s19, 0x6000
	v_add_u32_e32 v110, s19, v142
	ds_read_b128 v[106:109], v110
	v_mfma_f32_16x16x32_bf16 v[86:89], v[10:13], v[26:29], v[86:89]
	ds_read_b128 v[144:147], v110 offset:1024
	s_add_i32 s26, s8, -2
	s_and_b32 s28, s26, 3
	s_mulk_i32 s28, 0x6000
	v_add_u32_e32 v127, s28, v140
	v_add_u32_e32 v143, s28, v141
	v_mfma_f32_16x16x32_bf16 v[70:73], v[14:17], v[26:29], v[70:73]
	ds_read_b128 v[118:121], v127
	v_mfma_f32_16x16x32_bf16 v[90:93], v[2:5], v[22:25], v[90:93]
	ds_read_b128 v[114:117], v127 offset:1024
	v_mfma_f32_16x16x32_bf16 v[78:81], v[6:9], v[22:25], v[78:81]
	ds_read_b128 v[110:113], v127 offset:2048
	v_mfma_f32_16x16x32_bf16 v[62:65], v[10:13], v[22:25], v[62:65]
	v_mfma_f32_16x16x32_bf16 v[50:53], v[14:17], v[22:25], v[50:53]
	s_waitcnt vmcnt(0)
	s_waitcnt lgkmcnt(0)
	s_barrier
	v_mfma_f32_16x16x32_bf16 v[74:77], v[2:5], v[106:109], v[74:77]
	ds_read_b128 v[26:29], v143
	v_mfma_f32_16x16x32_bf16 v[58:61], v[6:9], v[106:109], v[58:61]
	ds_read_b128 v[22:25], v143 offset:1024
	v_mfma_f32_16x16x32_bf16 v[38:41], v[10:13], v[106:109], v[38:41]
	v_mfma_f32_16x16x32_bf16 v[30:33], v[14:17], v[106:109], v[30:33]
	ds_read_b128 v[106:109], v127 offset:3072
	v_mfma_f32_16x16x32_bf16 v[94:97], v[2:5], v[144:147], v[94:97]
	v_mfma_f32_16x16x32_bf16 v[82:85], v[6:9], v[144:147], v[82:85]
	v_mfma_f32_16x16x32_bf16 v[66:69], v[10:13], v[144:147], v[66:69]
	v_mfma_f32_16x16x32_bf16 v[34:37], v[14:17], v[144:147], v[34:37]
	s_waitcnt lgkmcnt(0)
	v_mfma_f32_16x16x32_bf16 v[102:105], v[118:121], v[26:29], v[102:105]
	v_mfma_f32_16x16x32_bf16 v[98:101], v[114:117], v[26:29], v[98:101]
	v_add_u32_e32 v132, s28, v142
	ds_read_b128 v[144:147], v132
	v_mfma_f32_16x16x32_bf16 v[86:89], v[110:113], v[26:29], v[86:89]
	ds_read_b128 v[122:125], v132 offset:1024
	v_mfma_f32_16x16x32_bf16 v[70:73], v[106:109], v[26:29], v[70:73]
	v_mfma_f32_16x16x32_bf16 v[90:93], v[118:121], v[22:25], v[90:93]
	v_mfma_f32_16x16x32_bf16 v[78:81], v[114:117], v[22:25], v[78:81]
	v_mfma_f32_16x16x32_bf16 v[62:65], v[110:113], v[22:25], v[62:65]
	v_mfma_f32_16x16x32_bf16 v[50:53], v[106:109], v[22:25], v[50:53]
	s_waitcnt vmcnt(0)
	s_waitcnt lgkmcnt(0)
	s_barrier
	v_mfma_f32_16x16x32_bf16 v[74:77], v[118:121], v[144:147], v[74:77]
	v_mfma_f32_16x16x32_bf16 v[58:61], v[114:117], v[144:147], v[58:61]
	v_mfma_f32_16x16x32_bf16 v[38:41], v[110:113], v[144:147], v[38:41]
	v_mfma_f32_16x16x32_bf16 v[30:33], v[106:109], v[144:147], v[30:33]
	s_add_u32 s20, s20, 0x80
	s_addc_u32 s21, s21, 0
	s_add_i32 s8, s8, 2
	s_cmpk_gt_u32 s17, 0x55
	v_mfma_f32_16x16x32_bf16 v[94:97], v[118:121], v[122:125], v[94:97]
	v_mfma_f32_16x16x32_bf16 v[82:85], v[114:117], v[122:125], v[82:85]
	v_mfma_f32_16x16x32_bf16 v[66:69], v[110:113], v[122:125], v[66:69]
	v_mfma_f32_16x16x32_bf16 v[34:37], v[106:109], v[122:125], v[34:37]
	s_branch .LBB0_135

.Lgf_G3x_top:
	s_waitcnt vmcnt(3)
	s_waitcnt lgkmcnt(0)
	s_barrier
	v_mfma_f32_16x16x32_bf16 v[102:105], v[2:5], v[26:29], v[102:105]
	v_mfma_f32_16x16x32_bf16 v[98:101], v[6:9], v[26:29], v[98:101]
	s_add_i32 s17, s8, -3
	s_and_b32 s19, s17, 2
	s_mulk_i32 s19, 0x6000
	v_add_u32_e32 v110, s19, v142
	ds_read_b128 v[106:109], v110
	v_mfma_f32_16x16x32_bf16 v[86:89], v[10:13], v[26:29], v[86:89]
	ds_read_b128 v[144:147], v110 offset:1024
	s_and_b32 s69, s8, 3
	s_mulk_i32 s69, 0x6000
	s_add_i32 s69, s69, s29
	s_mov_b32 m0, s69
	s_add_i32 s26, s8, -2
	s_and_b32 s28, s26, 3
	s_mulk_i32 s28, 0x6000
	v_add_u32_e32 v127, s28, v140
	v_add_u32_e32 v143, s28, v141
	v_mfma_f32_16x16x32_bf16 v[70:73], v[14:17], v[26:29], v[70:73]
	ds_read_b128 v[118:121], v127
	v_mfma_f32_16x16x32_bf16 v[90:93], v[2:5], v[22:25], v[90:93]
	ds_read_b128 v[114:117], v127 offset:1024
	global_load_lds_dwordx4 v126, s[44:45]
	s_add_i32 m0, s69, 0x2000
	v_mfma_f32_16x16x32_bf16 v[78:81], v[6:9], v[22:25], v[78:81]
	ds_read_b128 v[110:113], v127 offset:2048
	global_load_lds_dwordx4 v128, s[44:45]
	s_add_i32 m0, s69, 0x4000
	v_mfma_f32_16x16x32_bf16 v[62:65], v[10:13], v[22:25], v[62:65]
	global_load_lds_dwordx4 v130, s[30:31]
	s_add_u32 s44, s44, 64
	s_addc_u32 s45, s45, 0
	s_add_u32 s30, s30, 64
	s_addc_u32 s31, s31, 0
	v_mfma_f32_16x16x32_bf16 v[46:49], v[14:17], v[22:25], v[46:49]
	s_waitcnt lgkmcnt(0)
	v_mfma_f32_16x16x32_bf16 v[74:77], v[2:5], v[106:109], v[74:77]
	ds_read_b128 v[26:29], v143
	v_mfma_f32_16x16x32_bf16 v[58:61], v[6:9], v[106:109], v[58:61]
	ds_read_b128 v[22:25], v143 offset:1024
	v_mfma_f32_16x16x32_bf16 v[38:41], v[10:13], v[106:109], v[38:41]
	v_mfma_f32_16x16x32_bf16 v[30:33], v[14:17], v[106:109], v[30:33]
	ds_read_b128 v[106:109], v127 offset:3072
	v_mfma_f32_16x16x32_bf16 v[94:97], v[2:5], v[144:147], v[94:97]
	v_mfma_f32_16x16x32_bf16 v[82:85], v[6:9], v[144:147], v[82:85]
	v_mfma_f32_16x16x32_bf16 v[66:69], v[10:13], v[144:147], v[66:69]
	v_mfma_f32_16x16x32_bf16 v[34:37], v[14:17], v[144:147], v[34:37]
	s_waitcnt vmcnt(3)
	s_waitcnt lgkmcnt(0)
	s_barrier
	v_mfma_f32_16x16x32_bf16 v[102:105], v[118:121], v[26:29], v[102:105]
	v_mfma_f32_16x16x32_bf16 v[98:101], v[114:117], v[26:29], v[98:101]
	v_add_u32_e32 v132, s28, v142
	ds_read_b128 v[144:147], v132
	v_mfma_f32_16x16x32_bf16 v[86:89], v[110:113], v[26:29], v[86:89]
	ds_read_b128 v[122:125], v132 offset:1024
	s_add_i32 s69, s19, s29
	s_mov_b32 m0, s69
	s_add_i32 s19, s8, -1
	s_and_b32 s19, s19, 2
	s_mulk_i32 s19, 0x6000
	v_add_u32_e32 v127, s19, v140
	v_add_u32_e32 v132, s19, v141
	v_mfma_f32_16x16x32_bf16 v[70:73], v[106:109], v[26:29], v[70:73]
	ds_read_b128 v[2:5], v127
	v_mfma_f32_16x16x32_bf16 v[90:93], v[118:121], v[22:25], v[90:93]
	ds_read_b128 v[6:9], v127 offset:1024
	global_load_lds_dwordx4 v126, s[44:45]
	s_add_i32 m0, s69, 0x2000
	v_mfma_f32_16x16x32_bf16 v[78:81], v[114:117], v[22:25], v[78:81]
	ds_read_b128 v[10:13], v127 offset:2048
	global_load_lds_dwordx4 v128, s[44:45]
	s_add_i32 m0, s69, 0x4000
	v_mfma_f32_16x16x32_bf16 v[62:65], v[110:113], v[22:25], v[62:65]
	ds_read_b128 v[14:17], v127 offset:3072
	global_load_lds_dwordx4 v130, s[30:31]
	s_add_u32 s44, s44, 64
	s_addc_u32 s45, s45, 0
	s_add_u32 s30, s30, 64
	s_addc_u32 s31, s31, 0
	v_mfma_f32_16x16x32_bf16 v[46:49], v[106:109], v[22:25], v[46:49]
	s_waitcnt lgkmcnt(0)
	v_mfma_f32_16x16x32_bf16 v[74:77], v[118:121], v[144:147], v[74:77]
	ds_read_b128 v[26:29], v132
	v_mfma_f32_16x16x32_bf16 v[58:61], v[114:117], v[144:147], v[58:61]
	ds_read_b128 v[22:25], v132 offset:1024
	v_mfma_f32_16x16x32_bf16 v[38:41], v[110:113], v[144:147], v[38:41]
	v_mfma_f32_16x16x32_bf16 v[30:33], v[106:109], v[144:147], v[30:33]
	s_add_u32 s20, s20, 0x80
	s_addc_u32 s21, s21, 0
	s_add_i32 s8, s8, 2
	s_cmp_gt_u32 s17, 29
	v_mfma_f32_16x16x32_bf16 v[94:97], v[118:121], v[122:125], v[94:97]
	v_mfma_f32_16x16x32_bf16 v[82:85], v[114:117], v[122:125], v[82:85]
	v_mfma_f32_16x16x32_bf16 v[66:69], v[110:113], v[122:125], v[66:69]
	v_mfma_f32_16x16x32_bf16 v[34:37], v[106:109], v[122:125], v[34:37]
	s_cmp_lt_u32 s8, 30
	s_cbranch_scc1 .Lgf_G3x_top
	s_waitcnt vmcnt(3)
	s_waitcnt lgkmcnt(0)
	s_barrier
	v_mfma_f32_16x16x32_bf16 v[102:105], v[2:5], v[26:29], v[102:105]
	v_mfma_f32_16x16x32_bf16 v[98:101], v[6:9], v[26:29], v[98:101]
	s_add_i32 s17, s8, -3
	s_and_b32 s19, s17, 2
	s_mulk_i32 s19, 0x6000
	v_add_u32_e32 v110, s19, v142
	ds_read_b128 v[106:109], v110
	v_mfma_f32_16x16x32_bf16 v[86:89], v[10:13], v[26:29], v[86:89]
	ds_read_b128 v[144:147], v110 offset:1024
	s_and_b32 s69, s8, 3
	s_mulk_i32 s69, 0x6000
	s_add_i32 s69, s69, s29
	s_mov_b32 m0, s69
	s_add_i32 s26, s8, -2
	s_and_b32 s28, s26, 3
	s_mulk_i32 s28, 0x6000
	v_add_u32_e32 v127, s28, v140
	v_add_u32_e32 v143, s28, v141
	v_mfma_f32_16x16x32_bf16 v[70:73], v[14:17], v[26:29], v[70:73]
	ds_read_b128 v[118:121], v127
	v_mfma_f32_16x16x32_bf16 v[90:93], v[2:5], v[22:25], v[90:93]
	ds_read_b128 v[114:117], v127 offset:1024
	global_load_lds_dwordx4 v126, s[44:45]
	s_add_i32 m0, s69, 0x2000
	v_mfma_f32_16x16x32_bf16 v[78:81], v[6:9], v[22:25], v[78:81]
	ds_read_b128 v[110:113], v127 offset:2048
	global_load_lds_dwordx4 v128, s[44:45]
	s_add_i32 m0, s69, 0x4000
	v_mfma_f32_16x16x32_bf16 v[62:65], v[10:13], v[22:25], v[62:65]
	global_load_lds_dwordx4 v130, s[30:31]
	s_add_u32 s44, s44, 64
	s_addc_u32 s45, s45, 0
	s_add_u32 s30, s30, 64
	s_addc_u32 s31, s31, 0
	v_mfma_f32_16x16x32_bf16 v[46:49], v[14:17], v[22:25], v[46:49]
	s_waitcnt lgkmcnt(0)
	v_mfma_f32_16x16x32_bf16 v[74:77], v[2:5], v[106:109], v[74:77]
	ds_read_b128 v[26:29], v143
	v_mfma_f32_16x16x32_bf16 v[58:61], v[6:9], v[106:109], v[58:61]
	ds_read_b128 v[22:25], v143 offset:1024
	v_mfma_f32_16x16x32_bf16 v[38:41], v[10:13], v[106:109], v[38:41]
	v_mfma_f32_16x16x32_bf16 v[30:33], v[14:17], v[106:109], v[30:33]
	ds_read_b128 v[106:109], v127 offset:3072
	v_mfma_f32_16x16x32_bf16 v[94:97], v[2:5], v[144:147], v[94:97]
	v_mfma_f32_16x16x32_bf16 v[82:85], v[6:9], v[144:147], v[82:85]
	v_mfma_f32_16x16x32_bf16 v[66:69], v[10:13], v[144:147], v[66:69]
	v_mfma_f32_16x16x32_bf16 v[34:37], v[14:17], v[144:147], v[34:37]
	s_waitcnt vmcnt(3)
	s_waitcnt lgkmcnt(0)
	s_barrier
	v_mfma_f32_16x16x32_bf16 v[102:105], v[118:121], v[26:29], v[102:105]
	v_mfma_f32_16x16x32_bf16 v[98:101], v[114:117], v[26:29], v[98:101]
	v_add_u32_e32 v132, s28, v142
	ds_read_b128 v[144:147], v132
	v_mfma_f32_16x16x32_bf16 v[86:89], v[110:113], v[26:29], v[86:89]
	ds_read_b128 v[122:125], v132 offset:1024
	s_add_i32 s19, s8, -1
	s_and_b32 s19, s19, 2
	s_mulk_i32 s19, 0x6000
	v_add_u32_e32 v127, s19, v140
	v_add_u32_e32 v132, s19, v141
	v_mfma_f32_16x16x32_bf16 v[70:73], v[106:109], v[26:29], v[70:73]
	ds_read_b128 v[2:5], v127
	v_mfma_f32_16x16x32_bf16 v[90:93], v[118:121], v[22:25], v[90:93]
	ds_read_b128 v[6:9], v127 offset:1024
	v_mfma_f32_16x16x32_bf16 v[78:81], v[114:117], v[22:25], v[78:81]
	ds_read_b128 v[10:13], v127 offset:2048
	v_mfma_f32_16x16x32_bf16 v[62:65], v[110:113], v[22:25], v[62:65]
	ds_read_b128 v[14:17], v127 offset:3072
	v_mfma_f32_16x16x32_bf16 v[46:49], v[106:109], v[22:25], v[46:49]
	s_waitcnt lgkmcnt(0)
	v_mfma_f32_16x16x32_bf16 v[74:77], v[118:121], v[144:147], v[74:77]
	ds_read_b128 v[26:29], v132
	v_mfma_f32_16x16x32_bf16 v[58:61], v[114:117], v[144:147], v[58:61]
	ds_read_b128 v[22:25], v132 offset:1024
	v_mfma_f32_16x16x32_bf16 v[38:41], v[110:113], v[144:147], v[38:41]
	v_mfma_f32_16x16x32_bf16 v[30:33], v[106:109], v[144:147], v[30:33]
	s_add_u32 s20, s20, 0x80
	s_addc_u32 s21, s21, 0
	s_add_i32 s8, s8, 2
	s_cmp_gt_u32 s17, 29
	v_mfma_f32_16x16x32_bf16 v[94:97], v[118:121], v[122:125], v[94:97]
	v_mfma_f32_16x16x32_bf16 v[82:85], v[114:117], v[122:125], v[82:85]
	v_mfma_f32_16x16x32_bf16 v[66:69], v[110:113], v[122:125], v[66:69]
	v_mfma_f32_16x16x32_bf16 v[34:37], v[106:109], v[122:125], v[34:37]
	s_waitcnt vmcnt(0)
	s_waitcnt lgkmcnt(0)
	s_barrier
	v_mfma_f32_16x16x32_bf16 v[102:105], v[2:5], v[26:29], v[102:105]
	v_mfma_f32_16x16x32_bf16 v[98:101], v[6:9], v[26:29], v[98:101]
	s_add_i32 s17, s8, -3
	s_and_b32 s19, s17, 2
	s_mulk_i32 s19, 0x6000
	v_add_u32_e32 v110, s19, v142
	ds_read_b128 v[106:109], v110
	v_mfma_f32_16x16x32_bf16 v[86:89], v[10:13], v[26:29], v[86:89]
	ds_read_b128 v[144:147], v110 offset:1024
	s_add_i32 s26, s8, -2
	s_and_b32 s28, s26, 3
	s_mulk_i32 s28, 0x6000
	v_add_u32_e32 v127, s28, v140
	v_add_u32_e32 v143, s28, v141
	v_mfma_f32_16x16x32_bf16 v[70:73], v[14:17], v[26:29], v[70:73]
	ds_read_b128 v[118:121], v127
	v_mfma_f32_16x16x32_bf16 v[90:93], v[2:5], v[22:25], v[90:93]
	ds_read_b128 v[114:117], v127 offset:1024
	v_mfma_f32_16x16x32_bf16 v[78:81], v[6:9], v[22:25], v[78:81]
	ds_read_b128 v[110:113], v127 offset:2048
	v_mfma_f32_16x16x32_bf16 v[62:65], v[10:13], v[22:25], v[62:65]
	v_mfma_f32_16x16x32_bf16 v[46:49], v[14:17], v[22:25], v[46:49]
	s_waitcnt lgkmcnt(0)
	v_mfma_f32_16x16x32_bf16 v[74:77], v[2:5], v[106:109], v[74:77]
	ds_read_b128 v[26:29], v143
	v_mfma_f32_16x16x32_bf16 v[58:61], v[6:9], v[106:109], v[58:61]
	ds_read_b128 v[22:25], v143 offset:1024
	v_mfma_f32_16x16x32_bf16 v[38:41], v[10:13], v[106:109], v[38:41]
	v_mfma_f32_16x16x32_bf16 v[30:33], v[14:17], v[106:109], v[30:33]
	ds_read_b128 v[106:109], v127 offset:3072
	v_mfma_f32_16x16x32_bf16 v[94:97], v[2:5], v[144:147], v[94:97]
	v_mfma_f32_16x16x32_bf16 v[82:85], v[6:9], v[144:147], v[82:85]
	v_mfma_f32_16x16x32_bf16 v[66:69], v[10:13], v[144:147], v[66:69]
	v_mfma_f32_16x16x32_bf16 v[34:37], v[14:17], v[144:147], v[34:37]
	s_waitcnt vmcnt(0)
	s_waitcnt lgkmcnt(0)
	s_barrier
	v_mfma_f32_16x16x32_bf16 v[102:105], v[118:121], v[26:29], v[102:105]
	v_mfma_f32_16x16x32_bf16 v[98:101], v[114:117], v[26:29], v[98:101]
	v_add_u32_e32 v132, s28, v142
	ds_read_b128 v[144:147], v132
	v_mfma_f32_16x16x32_bf16 v[86:89], v[110:113], v[26:29], v[86:89]
	ds_read_b128 v[122:125], v132 offset:1024
	v_mfma_f32_16x16x32_bf16 v[70:73], v[106:109], v[26:29], v[70:73]
	v_mfma_f32_16x16x32_bf16 v[90:93], v[118:121], v[22:25], v[90:93]
	v_mfma_f32_16x16x32_bf16 v[78:81], v[114:117], v[22:25], v[78:81]
	v_mfma_f32_16x16x32_bf16 v[62:65], v[110:113], v[22:25], v[62:65]
	v_mfma_f32_16x16x32_bf16 v[46:49], v[106:109], v[22:25], v[46:49]
	s_waitcnt lgkmcnt(0)
	v_mfma_f32_16x16x32_bf16 v[74:77], v[118:121], v[144:147], v[74:77]
	v_mfma_f32_16x16x32_bf16 v[58:61], v[114:117], v[144:147], v[58:61]
	v_mfma_f32_16x16x32_bf16 v[38:41], v[110:113], v[144:147], v[38:41]
	v_mfma_f32_16x16x32_bf16 v[30:33], v[106:109], v[144:147], v[30:33]
	s_add_u32 s20, s20, 0x80
	s_addc_u32 s21, s21, 0
	s_add_i32 s8, s8, 2
	s_cmp_gt_u32 s17, 29
	v_mfma_f32_16x16x32_bf16 v[94:97], v[118:121], v[122:125], v[94:97]
	v_mfma_f32_16x16x32_bf16 v[82:85], v[114:117], v[122:125], v[82:85]
	v_mfma_f32_16x16x32_bf16 v[66:69], v[110:113], v[122:125], v[66:69]
	v_mfma_f32_16x16x32_bf16 v[34:37], v[106:109], v[122:125], v[34:37]
	s_branch .LBB0_305
.Lgr_G3x_entry:
	s_waitcnt vmcnt(3)
	s_waitcnt lgkmcnt(0)
	s_barrier
	v_mfma_f32_16x16x32_bf16 v[102:105], v[2:5], v[26:29], v[102:105]
	v_mfma_f32_16x16x32_bf16 v[98:101], v[6:9], v[26:29], v[98:101]
	s_add_i32 s17, s8, -3
	s_and_b32 s19, s17, 2
	s_mulk_i32 s19, 0x6000
	v_add_u32_e32 v110, s19, v142
	ds_read_b128 v[106:109], v110
	v_mfma_f32_16x16x32_bf16 v[86:89], v[10:13], v[26:29], v[86:89]
	ds_read_b128 v[144:147], v110 offset:1024
	s_and_b32 s69, s8, 3
	s_mulk_i32 s69, 0x6000
	s_add_i32 s69, s69, s29
	s_mov_b32 m0, s69
	s_add_i32 s26, s8, -2
	s_and_b32 s28, s26, 3
	s_mulk_i32 s28, 0x6000
	v_add_u32_e32 v127, s28, v140
	v_add_u32_e32 v143, s28, v141
	v_mfma_f32_16x16x32_bf16 v[70:73], v[14:17], v[26:29], v[70:73]
	ds_read_b128 v[118:121], v127
	v_mfma_f32_16x16x32_bf16 v[90:93], v[2:5], v[22:25], v[90:93]
	ds_read_b128 v[114:117], v127 offset:1024
	global_load_lds_dwordx4 v126, s[44:45]
	s_add_i32 m0, s69, 0x2000
	v_mfma_f32_16x16x32_bf16 v[78:81], v[6:9], v[22:25], v[78:81]
	ds_read_b128 v[110:113], v127 offset:2048
	global_load_lds_dwordx4 v128, s[44:45]
	s_add_i32 m0, s69, 0x4000
	v_mfma_f32_16x16x32_bf16 v[62:65], v[10:13], v[22:25], v[62:65]
	global_load_lds_dwordx4 v130, s[30:31]
	s_add_u32 s44, s44, 64
	s_addc_u32 s45, s45, 0
	s_add_u32 s30, s30, 64
	s_addc_u32 s31, s31, 0
	v_mfma_f32_16x16x32_bf16 v[46:49], v[14:17], v[22:25], v[46:49]
	s_waitcnt vmcnt(3)
	s_waitcnt lgkmcnt(0)
	s_barrier
	v_mfma_f32_16x16x32_bf16 v[74:77], v[2:5], v[106:109], v[74:77]
	ds_read_b128 v[26:29], v143
	v_mfma_f32_16x16x32_bf16 v[58:61], v[6:9], v[106:109], v[58:61]
	ds_read_b128 v[22:25], v143 offset:1024
	v_mfma_f32_16x16x32_bf16 v[38:41], v[10:13], v[106:109], v[38:41]
	v_mfma_f32_16x16x32_bf16 v[30:33], v[14:17], v[106:109], v[30:33]
	ds_read_b128 v[106:109], v127 offset:3072
	v_mfma_f32_16x16x32_bf16 v[94:97], v[2:5], v[144:147], v[94:97]
	v_mfma_f32_16x16x32_bf16 v[82:85], v[6:9], v[144:147], v[82:85]
	v_mfma_f32_16x16x32_bf16 v[66:69], v[10:13], v[144:147], v[66:69]
	v_mfma_f32_16x16x32_bf16 v[34:37], v[14:17], v[144:147], v[34:37]
	s_waitcnt lgkmcnt(0)
	v_mfma_f32_16x16x32_bf16 v[102:105], v[118:121], v[26:29], v[102:105]
	v_mfma_f32_16x16x32_bf16 v[98:101], v[114:117], v[26:29], v[98:101]
	v_add_u32_e32 v132, s28, v142
	ds_read_b128 v[144:147], v132
	v_mfma_f32_16x16x32_bf16 v[86:89], v[110:113], v[26:29], v[86:89]
	ds_read_b128 v[122:125], v132 offset:1024
	s_add_i32 s69, s19, s29
	s_mov_b32 m0, s69
	s_add_i32 s19, s8, -1
	s_and_b32 s19, s19, 2
	s_mulk_i32 s19, 0x6000
	v_add_u32_e32 v127, s19, v140
	v_add_u32_e32 v132, s19, v141
	v_mfma_f32_16x16x32_bf16 v[70:73], v[106:109], v[26:29], v[70:73]
	ds_read_b128 v[2:5], v127
	v_mfma_f32_16x16x32_bf16 v[90:93], v[118:121], v[22:25], v[90:93]
	ds_read_b128 v[6:9], v127 offset:1024
	global_load_lds_dwordx4 v126, s[44:45]
	s_add_i32 m0, s69, 0x2000
	v_mfma_f32_16x16x32_bf16 v[78:81], v[114:117], v[22:25], v[78:81]
	ds_read_b128 v[10:13], v127 offset:2048
	global_load_lds_dwordx4 v128, s[44:45]
	s_add_i32 m0, s69, 0x4000
	v_mfma_f32_16x16x32_bf16 v[62:65], v[110:113], v[22:25], v[62:65]
	ds_read_b128 v[14:17], v127 offset:3072
	global_load_lds_dwordx4 v130, s[30:31]
	s_add_u32 s44, s44, 64
	s_addc_u32 s45, s45, 0
	s_add_u32 s30, s30, 64
	s_addc_u32 s31, s31, 0
	v_mfma_f32_16x16x32_bf16 v[46:49], v[106:109], v[22:25], v[46:49]
.Lgr_G3x_top:
	s_waitcnt vmcnt(3)
	s_waitcnt lgkmcnt(0)
	s_barrier
	v_mfma_f32_16x16x32_bf16 v[74:77], v[118:121], v[144:147], v[74:77]
	ds_read_b128 v[26:29], v132
	v_mfma_f32_16x16x32_bf16 v[58:61], v[114:117], v[144:147], v[58:61]
	ds_read_b128 v[22:25], v132 offset:1024
	v_mfma_f32_16x16x32_bf16 v[38:41], v[110:113], v[144:147], v[38:41]
	v_mfma_f32_16x16x32_bf16 v[30:33], v[106:109], v[144:147], v[30:33]
	s_add_u32 s20, s20, 0x80
	s_addc_u32 s21, s21, 0
	s_add_i32 s8, s8, 2
	s_cmp_gt_u32 s17, 29
	v_mfma_f32_16x16x32_bf16 v[94:97], v[118:121], v[122:125], v[94:97]
	v_mfma_f32_16x16x32_bf16 v[82:85], v[114:117], v[122:125], v[82:85]
	v_mfma_f32_16x16x32_bf16 v[66:69], v[110:113], v[122:125], v[66:69]
	v_mfma_f32_16x16x32_bf16 v[34:37], v[106:109], v[122:125], v[34:37]
	s_cmp_lt_u32 s8, 30
	s_cbranch_scc0 .Lgr_G3x_tail
	s_waitcnt lgkmcnt(0)
	v_mfma_f32_16x16x32_bf16 v[102:105], v[2:5], v[26:29], v[102:105]
	v_mfma_f32_16x16x32_bf16 v[98:101], v[6:9], v[26:29], v[98:101]
	s_add_i32 s17, s8, -3
	s_and_b32 s19, s17, 2
	s_mulk_i32 s19, 0x6000
	v_add_u32_e32 v110, s19, v142
	ds_read_b128 v[106:109], v110
	v_mfma_f32_16x16x32_bf16 v[86:89], v[10:13], v[26:29], v[86:89]
	ds_read_b128 v[144:147], v110 offset:1024
	s_and_b32 s69, s8, 3
	s_mulk_i32 s69, 0x6000
	s_add_i32 s69, s69, s29
	s_mov_b32 m0, s69
	s_add_i32 s26, s8, -2
	s_and_b32 s28, s26, 3
	s_mulk_i32 s28, 0x6000
	v_add_u32_e32 v127, s28, v140
	v_add_u32_e32 v143, s28, v141
	v_mfma_f32_16x16x32_bf16 v[70:73], v[14:17], v[26:29], v[70:73]
	ds_read_b128 v[118:121], v127
	v_mfma_f32_16x16x32_bf16 v[90:93], v[2:5], v[22:25], v[90:93]
	ds_read_b128 v[114:117], v127 offset:1024
	global_load_lds_dwordx4 v126, s[44:45]
	s_add_i32 m0, s69, 0x2000
	v_mfma_f32_16x16x32_bf16 v[78:81], v[6:9], v[22:25], v[78:81]
	ds_read_b128 v[110:113], v127 offset:2048
	global_load_lds_dwordx4 v128, s[44:45]
	s_add_i32 m0, s69, 0x4000
	v_mfma_f32_16x16x32_bf16 v[62:65], v[10:13], v[22:25], v[62:65]
	global_load_lds_dwordx4 v130, s[30:31]
	s_add_u32 s44, s44, 64
	s_addc_u32 s45, s45, 0
	s_add_u32 s30, s30, 64
	s_addc_u32 s31, s31, 0
	v_mfma_f32_16x16x32_bf16 v[46:49], v[14:17], v[22:25], v[46:49]
	s_waitcnt vmcnt(3)
	s_waitcnt lgkmcnt(0)
	s_barrier
	v_mfma_f32_16x16x32_bf16 v[74:77], v[2:5], v[106:109], v[74:77]
	ds_read_b128 v[26:29], v143
	v_mfma_f32_16x16x32_bf16 v[58:61], v[6:9], v[106:109], v[58:61]
	ds_read_b128 v[22:25], v143 offset:1024
	v_mfma_f32_16x16x32_bf16 v[38:41], v[10:13], v[106:109], v[38:41]
	v_mfma_f32_16x16x32_bf16 v[30:33], v[14:17], v[106:109], v[30:33]
	ds_read_b128 v[106:109], v127 offset:3072
	v_mfma_f32_16x16x32_bf16 v[94:97], v[2:5], v[144:147], v[94:97]
	v_mfma_f32_16x16x32_bf16 v[82:85], v[6:9], v[144:147], v[82:85]
	v_mfma_f32_16x16x32_bf16 v[66:69], v[10:13], v[144:147], v[66:69]
	v_mfma_f32_16x16x32_bf16 v[34:37], v[14:17], v[144:147], v[34:37]
	s_waitcnt lgkmcnt(0)
	v_mfma_f32_16x16x32_bf16 v[102:105], v[118:121], v[26:29], v[102:105]
	v_mfma_f32_16x16x32_bf16 v[98:101], v[114:117], v[26:29], v[98:101]
	v_add_u32_e32 v132, s28, v142
	ds_read_b128 v[144:147], v132
	v_mfma_f32_16x16x32_bf16 v[86:89], v[110:113], v[26:29], v[86:89]
	ds_read_b128 v[122:125], v132 offset:1024
	s_add_i32 s69, s19, s29
	s_mov_b32 m0, s69
	s_add_i32 s19, s8, -1
	s_and_b32 s19, s19, 2
	s_mulk_i32 s19, 0x6000
	v_add_u32_e32 v127, s19, v140
	v_add_u32_e32 v132, s19, v141
	v_mfma_f32_16x16x32_bf16 v[70:73], v[106:109], v[26:29], v[70:73]
	ds_read_b128 v[2:5], v127
	v_mfma_f32_16x16x32_bf16 v[90:93], v[118:121], v[22:25], v[90:93]
	ds_read_b128 v[6:9], v127 offset:1024
	global_load_lds_dwordx4 v126, s[44:45]
	s_add_i32 m0, s69, 0x2000
	v_mfma_f32_16x16x32_bf16 v[78:81], v[114:117], v[22:25], v[78:81]
	ds_read_b128 v[10:13], v127 offset:2048
	global_load_lds_dwordx4 v128, s[44:45]
	s_add_i32 m0, s69, 0x4000
	v_mfma_f32_16x16x32_bf16 v[62:65], v[110:113], v[22:25], v[62:65]
	ds_read_b128 v[14:17], v127 offset:3072
	global_load_lds_dwordx4 v130, s[30:31]
	s_add_u32 s44, s44, 64
	s_addc_u32 s45, s45, 0
	s_add_u32 s30, s30, 64
	s_addc_u32 s31, s31, 0
	v_mfma_f32_16x16x32_bf16 v[46:49], v[106:109], v[22:25], v[46:49]
	s_branch .Lgr_G3x_top
.Lgr_G3x_tail:
	s_waitcnt lgkmcnt(0)
	v_mfma_f32_16x16x32_bf16 v[102:105], v[2:5], v[26:29], v[102:105]
	v_mfma_f32_16x16x32_bf16 v[98:101], v[6:9], v[26:29], v[98:101]
	s_add_i32 s17, s8, -3
	s_and_b32 s19, s17, 2
	s_mulk_i32 s19, 0x6000
	v_add_u32_e32 v110, s19, v142
	ds_read_b128 v[106:109], v110
	v_mfma_f32_16x16x32_bf16 v[86:89], v[10:13], v[26:29], v[86:89]
	ds_read_b128 v[144:147], v110 offset:1024
	s_and_b32 s69, s8, 3
	s_mulk_i32 s69, 0x6000
	s_add_i32 s69, s69, s29
	s_mov_b32 m0, s69
	s_add_i32 s26, s8, -2
	s_and_b32 s28, s26, 3
	s_mulk_i32 s28, 0x6000
	v_add_u32_e32 v127, s28, v140
	v_add_u32_e32 v143, s28, v141
	v_mfma_f32_16x16x32_bf16 v[70:73], v[14:17], v[26:29], v[70:73]
	ds_read_b128 v[118:121], v127
	v_mfma_f32_16x16x32_bf16 v[90:93], v[2:5], v[22:25], v[90:93]
	ds_read_b128 v[114:117], v127 offset:1024
	global_load_lds_dwordx4 v126, s[44:45]
	s_add_i32 m0, s69, 0x2000
	v_mfma_f32_16x16x32_bf16 v[78:81], v[6:9], v[22:25], v[78:81]
	ds_read_b128 v[110:113], v127 offset:2048
	global_load_lds_dwordx4 v128, s[44:45]
	s_add_i32 m0, s69, 0x4000
	v_mfma_f32_16x16x32_bf16 v[62:65], v[10:13], v[22:25], v[62:65]
	global_load_lds_dwordx4 v130, s[30:31]
	s_add_u32 s44, s44, 64
	s_addc_u32 s45, s45, 0
	s_add_u32 s30, s30, 64
	s_addc_u32 s31, s31, 0
	v_mfma_f32_16x16x32_bf16 v[46:49], v[14:17], v[22:25], v[46:49]
	s_waitcnt vmcnt(3)
	s_waitcnt lgkmcnt(0)
	s_barrier
	v_mfma_f32_16x16x32_bf16 v[74:77], v[2:5], v[106:109], v[74:77]
	ds_read_b128 v[26:29], v143
	v_mfma_f32_16x16x32_bf16 v[58:61], v[6:9], v[106:109], v[58:61]
	ds_read_b128 v[22:25], v143 offset:1024
	v_mfma_f32_16x16x32_bf16 v[38:41], v[10:13], v[106:109], v[38:41]
	v_mfma_f32_16x16x32_bf16 v[30:33], v[14:17], v[106:109], v[30:33]
	ds_read_b128 v[106:109], v127 offset:3072
	v_mfma_f32_16x16x32_bf16 v[94:97], v[2:5], v[144:147], v[94:97]
	v_mfma_f32_16x16x32_bf16 v[82:85], v[6:9], v[144:147], v[82:85]
	v_mfma_f32_16x16x32_bf16 v[66:69], v[10:13], v[144:147], v[66:69]
	v_mfma_f32_16x16x32_bf16 v[34:37], v[14:17], v[144:147], v[34:37]
	s_waitcnt lgkmcnt(0)
	v_mfma_f32_16x16x32_bf16 v[102:105], v[118:121], v[26:29], v[102:105]
	v_mfma_f32_16x16x32_bf16 v[98:101], v[114:117], v[26:29], v[98:101]
	v_add_u32_e32 v132, s28, v142
	ds_read_b128 v[144:147], v132
	v_mfma_f32_16x16x32_bf16 v[86:89], v[110:113], v[26:29], v[86:89]
	ds_read_b128 v[122:125], v132 offset:1024
	s_add_i32 s19, s8, -1
	s_and_b32 s19, s19, 2
	s_mulk_i32 s19, 0x6000
	v_add_u32_e32 v127, s19, v140
	v_add_u32_e32 v132, s19, v141
	v_mfma_f32_16x16x32_bf16 v[70:73], v[106:109], v[26:29], v[70:73]
	ds_read_b128 v[2:5], v127
	v_mfma_f32_16x16x32_bf16 v[90:93], v[118:121], v[22:25], v[90:93]
	ds_read_b128 v[6:9], v127 offset:1024
	v_mfma_f32_16x16x32_bf16 v[78:81], v[114:117], v[22:25], v[78:81]
	ds_read_b128 v[10:13], v127 offset:2048
	v_mfma_f32_16x16x32_bf16 v[62:65], v[110:113], v[22:25], v[62:65]
	ds_read_b128 v[14:17], v127 offset:3072
	v_mfma_f32_16x16x32_bf16 v[46:49], v[106:109], v[22:25], v[46:49]
	s_waitcnt vmcnt(0)
	s_waitcnt lgkmcnt(0)
	s_barrier
	v_mfma_f32_16x16x32_bf16 v[74:77], v[118:121], v[144:147], v[74:77]
	ds_read_b128 v[26:29], v132
	v_mfma_f32_16x16x32_bf16 v[58:61], v[114:117], v[144:147], v[58:61]
	ds_read_b128 v[22:25], v132 offset:1024
	v_mfma_f32_16x16x32_bf16 v[38:41], v[110:113], v[144:147], v[38:41]
	v_mfma_f32_16x16x32_bf16 v[30:33], v[106:109], v[144:147], v[30:33]
	s_add_u32 s20, s20, 0x80
	s_addc_u32 s21, s21, 0
	s_add_i32 s8, s8, 2
	s_cmp_gt_u32 s17, 29
	v_mfma_f32_16x16x32_bf16 v[94:97], v[118:121], v[122:125], v[94:97]
	v_mfma_f32_16x16x32_bf16 v[82:85], v[114:117], v[122:125], v[82:85]
	v_mfma_f32_16x16x32_bf16 v[66:69], v[110:113], v[122:125], v[66:69]
	v_mfma_f32_16x16x32_bf16 v[34:37], v[106:109], v[122:125], v[34:37]
	s_waitcnt lgkmcnt(0)
	v_mfma_f32_16x16x32_bf16 v[102:105], v[2:5], v[26:29], v[102:105]
	v_mfma_f32_16x16x32_bf16 v[98:101], v[6:9], v[26:29], v[98:101]
	s_add_i32 s17, s8, -3
	s_and_b32 s19, s17, 2
	s_mulk_i32 s19, 0x6000
	v_add_u32_e32 v110, s19, v142
	ds_read_b128 v[106:109], v110
	v_mfma_f32_16x16x32_bf16 v[86:89], v[10:13], v[26:29], v[86:89]
	ds_read_b128 v[144:147], v110 offset:1024
	s_add_i32 s26, s8, -2
	s_and_b32 s28, s26, 3
	s_mulk_i32 s28, 0x6000
	v_add_u32_e32 v127, s28, v140
	v_add_u32_e32 v143, s28, v141
	v_mfma_f32_16x16x32_bf16 v[70:73], v[14:17], v[26:29], v[70:73]
	ds_read_b128 v[118:121], v127
	v_mfma_f32_16x16x32_bf16 v[90:93], v[2:5], v[22:25], v[90:93]
	ds_read_b128 v[114:117], v127 offset:1024
	v_mfma_f32_16x16x32_bf16 v[78:81], v[6:9], v[22:25], v[78:81]
	ds_read_b128 v[110:113], v127 offset:2048
	v_mfma_f32_16x16x32_bf16 v[62:65], v[10:13], v[22:25], v[62:65]
	v_mfma_f32_16x16x32_bf16 v[46:49], v[14:17], v[22:25], v[46:49]
	s_waitcnt vmcnt(0)
	s_waitcnt lgkmcnt(0)
	s_barrier
	v_mfma_f32_16x16x32_bf16 v[74:77], v[2:5], v[106:109], v[74:77]
	ds_read_b128 v[26:29], v143
	v_mfma_f32_16x16x32_bf16 v[58:61], v[6:9], v[106:109], v[58:61]
	ds_read_b128 v[22:25], v143 offset:1024
	v_mfma_f32_16x16x32_bf16 v[38:41], v[10:13], v[106:109], v[38:41]
	v_mfma_f32_16x16x32_bf16 v[30:33], v[14:17], v[106:109], v[30:33]
	ds_read_b128 v[106:109], v127 offset:3072
	v_mfma_f32_16x16x32_bf16 v[94:97], v[2:5], v[144:147], v[94:97]
	v_mfma_f32_16x16x32_bf16 v[82:85], v[6:9], v[144:147], v[82:85]
	v_mfma_f32_16x16x32_bf16 v[66:69], v[10:13], v[144:147], v[66:69]
	v_mfma_f32_16x16x32_bf16 v[34:37], v[14:17], v[144:147], v[34:37]
	s_waitcnt lgkmcnt(0)
	v_mfma_f32_16x16x32_bf16 v[102:105], v[118:121], v[26:29], v[102:105]
	v_mfma_f32_16x16x32_bf16 v[98:101], v[114:117], v[26:29], v[98:101]
	v_add_u32_e32 v132, s28, v142
	ds_read_b128 v[144:147], v132
	v_mfma_f32_16x16x32_bf16 v[86:89], v[110:113], v[26:29], v[86:89]
	ds_read_b128 v[122:125], v132 offset:1024
	v_mfma_f32_16x16x32_bf16 v[70:73], v[106:109], v[26:29], v[70:73]
	v_mfma_f32_16x16x32_bf16 v[90:93], v[118:121], v[22:25], v[90:93]
	v_mfma_f32_16x16x32_bf16 v[78:81], v[114:117], v[22:25], v[78:81]
	v_mfma_f32_16x16x32_bf16 v[62:65], v[110:113], v[22:25], v[62:65]
	v_mfma_f32_16x16x32_bf16 v[46:49], v[106:109], v[22:25], v[46:49]
	s_waitcnt vmcnt(0)
	s_waitcnt lgkmcnt(0)
	s_barrier
	v_mfma_f32_16x16x32_bf16 v[74:77], v[118:121], v[144:147], v[74:77]
	v_mfma_f32_16x16x32_bf16 v[58:61], v[114:117], v[144:147], v[58:61]
	v_mfma_f32_16x16x32_bf16 v[38:41], v[110:113], v[144:147], v[38:41]
	v_mfma_f32_16x16x32_bf16 v[30:33], v[106:109], v[144:147], v[30:33]
	s_add_u32 s20, s20, 0x80
	s_addc_u32 s21, s21, 0
	s_add_i32 s8, s8, 2
	s_cmp_gt_u32 s17, 29
	v_mfma_f32_16x16x32_bf16 v[94:97], v[118:121], v[122:125], v[94:97]
	v_mfma_f32_16x16x32_bf16 v[82:85], v[114:117], v[122:125], v[82:85]
	v_mfma_f32_16x16x32_bf16 v[66:69], v[110:113], v[122:125], v[66:69]
	v_mfma_f32_16x16x32_bf16 v[34:37], v[106:109], v[122:125], v[34:37]
	s_branch .LBB0_305
